# on v76: non-temporal hint also on P0's full-line stores (bf16 weight rows of the transposes, XN rows of the input LayerNorm)
# speedup vs baseline: 1.0197x; 1.0197x over previous
.LBB0_45:
	ds_read2_b32 v[94:95], v75 offset1:8
	ds_read2_b32 v[96:97], v75 offset0:33 offset1:41
	ds_read2_b32 v[98:99], v75 offset0:66 offset1:74
	ds_read2_b32 v[100:101], v75 offset0:99 offset1:107
	ds_read2_b32 v[102:103], v75 offset0:132 offset1:140
	s_waitcnt lgkmcnt(4)
	v_bfe_u32 v34, v94, 16, 1
	s_waitcnt lgkmcnt(3)
	v_bfe_u32 v89, v96, 16, 1
	v_add3_u32 v34, v94, v34, s37
	v_add3_u32 v89, v96, v89, s37
	v_lshrrev_b32_e32 v34, 16, v34
	ds_read2_b32 v[104:105], v75 offset0:165 offset1:173
	v_and_or_b32 v90, v89, s38, v34
	s_waitcnt lgkmcnt(3)
	v_bfe_u32 v34, v98, 16, 1
	v_add3_u32 v34, v98, v34, s37
	s_waitcnt lgkmcnt(2)
	v_bfe_u32 v89, v100, 16, 1
	ds_read2_b32 v[106:107], v75 offset0:198 offset1:206
	v_lshrrev_b32_e32 v34, 16, v34
	v_add3_u32 v89, v100, v89, s37
	ds_read2_b32 v[108:109], v75 offset0:231 offset1:239
	v_and_or_b32 v91, v89, s38, v34
	s_waitcnt lgkmcnt(3)
	v_bfe_u32 v34, v102, 16, 1
	v_add3_u32 v34, v102, v34, s37
	s_waitcnt lgkmcnt(2)
	v_bfe_u32 v89, v104, 16, 1
	v_lshrrev_b32_e32 v34, 16, v34
	v_add3_u32 v89, v104, v89, s37
	v_and_or_b32 v92, v89, s38, v34
	s_waitcnt lgkmcnt(1)
	v_bfe_u32 v34, v106, 16, 1
	v_add3_u32 v34, v106, v34, s37
	s_waitcnt lgkmcnt(0)
	v_bfe_u32 v89, v108, 16, 1
	v_lshrrev_b32_e32 v34, 16, v34
	v_add3_u32 v89, v108, v89, s37
	v_and_or_b32 v93, v89, s38, v34
	v_add_u32_e32 v34, s15, v74
	v_mad_i64_i32 v[110:111], s[12:13], v34, s36, 0
	s_ashr_i32 s5, s4, 31
	v_lshl_add_u64 v[110:111], v[110:111], 1, s[6:7]
	s_lshl_b64 s[12:13], s[4:5], 1
	v_lshl_add_u64 v[110:111], v[110:111], 0, s[12:13]
	v_lshlrev_b32_e32 v34, 1, v72
	v_lshl_add_u64 v[110:111], v[110:111], 0, v[34:35]
	v_bfe_u32 v89, v95, 16, 1
	global_store_dwordx4 v[110:111], v[90:93], off nt
	v_add3_u32 v89, v95, v89, s37
	v_lshrrev_b32_e32 v89, 16, v89
	v_bfe_u32 v90, v97, 16, 1
	v_add3_u32 v90, v97, v90, s37
	v_and_or_b32 v90, v90, s38, v89
	v_bfe_u32 v89, v99, 16, 1
	v_add3_u32 v89, v99, v89, s37
	v_bfe_u32 v91, v101, 16, 1
	v_lshrrev_b32_e32 v89, 16, v89
	v_add3_u32 v91, v101, v91, s37
	v_and_or_b32 v91, v91, s38, v89
	v_bfe_u32 v89, v103, 16, 1
	v_add3_u32 v89, v103, v89, s37
	v_bfe_u32 v92, v105, 16, 1
	v_lshrrev_b32_e32 v89, 16, v89
	v_add3_u32 v92, v105, v92, s37
	v_and_or_b32 v92, v92, s38, v89
	v_bfe_u32 v89, v107, 16, 1
	v_add3_u32 v89, v107, v89, s37
	v_bfe_u32 v93, v109, 16, 1
	v_lshrrev_b32_e32 v89, 16, v89
	v_add3_u32 v93, v109, v93, s37
	v_and_or_b32 v93, v93, s38, v89
	v_add_u32_e32 v89, s15, v76
	v_mad_i64_i32 v[94:95], s[26:27], v89, s36, 0
	v_lshl_add_u64 v[94:95], v[94:95], 1, s[6:7]
	v_lshl_add_u64 v[94:95], v[94:95], 0, s[12:13]
	ds_read2_b32 v[96:97], v75 offset0:16 offset1:24
	v_lshl_add_u64 v[94:95], v[94:95], 0, v[34:35]
	global_store_dwordx4 v[94:95], v[90:93], off nt
	ds_read2_b32 v[94:95], v75 offset0:49 offset1:57
	ds_read2_b32 v[98:99], v75 offset0:82 offset1:90
	ds_read2_b32 v[100:101], v75 offset0:115 offset1:123
	s_waitcnt lgkmcnt(3)
	v_bfe_u32 v89, v96, 16, 1
	v_add3_u32 v89, v96, v89, s37
	s_waitcnt lgkmcnt(2)
	v_bfe_u32 v90, v94, 16, 1
	ds_read2_b32 v[102:103], v75 offset0:148 offset1:156
	v_lshrrev_b32_e32 v89, 16, v89
	v_add3_u32 v90, v94, v90, s37
	ds_read2_b32 v[104:105], v75 offset0:181 offset1:189
	v_and_or_b32 v90, v90, s38, v89
	s_waitcnt lgkmcnt(3)
	v_bfe_u32 v89, v98, 16, 1
	v_add3_u32 v89, v98, v89, s37
	s_waitcnt lgkmcnt(2)
	v_bfe_u32 v91, v100, 16, 1
	ds_read2_b32 v[106:107], v75 offset0:214 offset1:222
	v_lshrrev_b32_e32 v89, 16, v89
	v_add3_u32 v91, v100, v91, s37
	ds_read2_b32 v[108:109], v75 offset0:247 offset1:255
	v_and_or_b32 v91, v91, s38, v89
	s_waitcnt lgkmcnt(3)
	v_bfe_u32 v89, v102, 16, 1
	v_add3_u32 v89, v102, v89, s37
	s_waitcnt lgkmcnt(2)
	v_bfe_u32 v92, v104, 16, 1
	v_lshrrev_b32_e32 v89, 16, v89
	v_add3_u32 v92, v104, v92, s37
	v_and_or_b32 v92, v92, s38, v89
	s_waitcnt lgkmcnt(1)
	v_bfe_u32 v89, v106, 16, 1
	v_add3_u32 v89, v106, v89, s37
	s_waitcnt lgkmcnt(0)
	v_bfe_u32 v93, v108, 16, 1
	v_lshrrev_b32_e32 v89, 16, v89
	v_add3_u32 v93, v108, v93, s37
	v_and_or_b32 v93, v93, s38, v89
	v_add_u32_e32 v89, s15, v77
	v_mad_i64_i32 v[110:111], s[26:27], v89, s36, 0
	v_lshl_add_u64 v[110:111], v[110:111], 1, s[6:7]
	v_lshl_add_u64 v[110:111], v[110:111], 0, s[12:13]
	v_lshl_add_u64 v[110:111], v[110:111], 0, v[34:35]
	v_bfe_u32 v89, v97, 16, 1
	global_store_dwordx4 v[110:111], v[90:93], off nt
	v_add3_u32 v89, v97, v89, s37
	v_lshrrev_b32_e32 v89, 16, v89
	v_bfe_u32 v90, v95, 16, 1
	v_add3_u32 v90, v95, v90, s37
	v_and_or_b32 v90, v90, s38, v89
	v_bfe_u32 v89, v99, 16, 1
	v_add3_u32 v89, v99, v89, s37
	v_bfe_u32 v91, v101, 16, 1
	v_lshrrev_b32_e32 v89, 16, v89
	v_add3_u32 v91, v101, v91, s37
	v_and_or_b32 v91, v91, s38, v89
	v_bfe_u32 v89, v103, 16, 1
	v_add3_u32 v89, v103, v89, s37
	v_bfe_u32 v92, v105, 16, 1
	v_lshrrev_b32_e32 v89, 16, v89
	v_add3_u32 v92, v105, v92, s37
	v_and_or_b32 v92, v92, s38, v89
	v_bfe_u32 v89, v107, 16, 1
	v_add3_u32 v89, v107, v89, s37
	v_bfe_u32 v93, v109, 16, 1
	v_lshrrev_b32_e32 v89, 16, v89
	v_add3_u32 v93, v109, v93, s37
	v_and_or_b32 v93, v93, s38, v89
	v_add_u32_e32 v89, s15, v78
	v_mad_i64_i32 v[94:95], s[26:27], v89, s36, 0
	v_lshl_add_u64 v[94:95], v[94:95], 1, s[6:7]
	v_lshl_add_u64 v[94:95], v[94:95], 0, s[12:13]
	v_lshl_add_u64 v[94:95], v[94:95], 0, v[34:35]
	global_store_dwordx4 v[94:95], v[90:93], off nt
	s_waitcnt lgkmcnt(0)
	s_andn2_b64 vcc, exec, s[24:25]
	s_cbranch_vccnz .LBB0_62
	s_add_i32 s5, s39, 0x1000
	s_cmpk_lt_i32 s39, 0x1900
	s_cselect_b64 s[26:27], -1, 0
	s_cmpk_gt_i32 s39, 0x18ff
	s_cselect_b64 s[24:25], -1, 0
	s_and_b64 vcc, exec, s[24:25]
	s_cbranch_vccnz .LBB0_59
	s_mov_b64 s[6:7], s[0:1]
	s_load_dwordx2 s[6:7], s[6:7], 0x80
	s_mul_hi_u32 s4, s5, 0xc7ce0c7d
	s_lshr_b32 s16, s4, 12
	s_mul_i32 s4, s16, 0x1480
	s_sub_i32 s15, s5, s4
	s_mul_i32 s12, s16, 0x1800000
	s_mul_hi_u32 s4, s16, 0x1800000
	s_waitcnt lgkmcnt(0)
	s_add_u32 s6, s6, s12
	s_addc_u32 s4, s7, s4
	s_add_u32 s30, s6, 0x200000
	s_addc_u32 s31, s4, 0
	s_cmpk_gt_u32 s15, 0x2ff
	s_mov_b64 s[12:13], -1
	s_cbranch_scc0 .LBB0_56
	s_cmpk_gt_u32 s15, 0x3ff
	s_cbranch_scc0 .LBB0_53
	s_cmpk_gt_u32 s15, 0xeff
	s_cbranch_scc0 .LBB0_51
	s_mov_b64 s[6:7], s[0:1]
	s_load_dwordx2 s[6:7], s[6:7], 0x60
	s_mul_i32 s12, s16, 0xb00000
	s_mul_hi_u32 s4, s16, 0xb00000
	s_waitcnt lgkmcnt(0)
	s_add_u32 s34, s6, s12
	s_addc_u32 s35, s7, s4
	s_add_u32 s6, s30, 0x1200000
	s_addc_u32 s7, s31, 0
	s_lshl_b32 s4, s15, 1
	s_lshl_b32 s12, s15, 5
	s_and_b32 s4, s4, 0x3fc0
	s_addk_i32 s4, 0xe200
	s_and_b32 s14, s12, 0x3e0
	s_mov_b64 s[12:13], 0

.LBB0_61:
	ds_read2_b32 v[86:87], v75 offset1:8
	ds_read2_b32 v[88:89], v75 offset0:33 offset1:41
	ds_read2_b32 v[90:91], v75 offset0:66 offset1:74
	ds_read2_b32 v[92:93], v75 offset0:99 offset1:107
	ds_read2_b32 v[94:95], v75 offset0:132 offset1:140
	s_waitcnt lgkmcnt(4)
	v_bfe_u32 v82, v86, 16, 1
	s_waitcnt lgkmcnt(3)
	v_bfe_u32 v83, v88, 16, 1
	v_add3_u32 v82, v86, v82, s37
	v_add3_u32 v83, v88, v83, s37
	v_lshrrev_b32_e32 v82, 16, v82
	ds_read2_b32 v[96:97], v75 offset0:165 offset1:173
	v_and_or_b32 v82, v83, s38, v82
	s_waitcnt lgkmcnt(3)
	v_bfe_u32 v83, v90, 16, 1
	v_add3_u32 v83, v90, v83, s37
	s_waitcnt lgkmcnt(2)
	v_bfe_u32 v84, v92, 16, 1
	ds_read2_b32 v[98:99], v75 offset0:198 offset1:206
	v_lshrrev_b32_e32 v83, 16, v83
	v_add3_u32 v84, v92, v84, s37
	ds_read2_b32 v[100:101], v75 offset0:231 offset1:239
	v_and_or_b32 v83, v84, s38, v83
	s_waitcnt lgkmcnt(3)
	v_bfe_u32 v84, v94, 16, 1
	v_add3_u32 v84, v94, v84, s37
	s_waitcnt lgkmcnt(2)
	v_bfe_u32 v85, v96, 16, 1
	v_lshrrev_b32_e32 v84, 16, v84
	v_add3_u32 v85, v96, v85, s37
	v_and_or_b32 v84, v85, s38, v84
	s_waitcnt lgkmcnt(1)
	v_bfe_u32 v85, v98, 16, 1
	v_add3_u32 v85, v98, v85, s37
	s_waitcnt lgkmcnt(0)
	v_bfe_u32 v86, v100, 16, 1
	v_lshrrev_b32_e32 v85, 16, v85
	v_add3_u32 v86, v100, v86, s37
	v_and_or_b32 v85, v86, s38, v85
	v_add_u32_e32 v86, s15, v74
	v_mad_i64_i32 v[102:103], s[12:13], v86, s41, 0
	s_ashr_i32 s21, s20, 31
	v_lshl_add_u64 v[102:103], v[102:103], 1, s[18:19]
	s_lshl_b64 s[12:13], s[20:21], 1
	v_lshl_add_u64 v[102:103], v[102:103], 0, s[12:13]
	v_lshl_add_u64 v[102:103], v[102:103], 0, v[34:35]
	global_store_dwordx4 v[102:103], v[82:85], off nt
	v_bfe_u32 v86, v101, 16, 1
	v_add3_u32 v86, v101, v86, s37
	v_bfe_u32 v82, v87, 16, 1
	v_add3_u32 v82, v87, v82, s37
	v_bfe_u32 v83, v89, 16, 1
	v_lshrrev_b32_e32 v82, 16, v82
	v_add3_u32 v83, v89, v83, s37
	v_and_or_b32 v82, v83, s38, v82
	v_bfe_u32 v83, v91, 16, 1
	v_add3_u32 v83, v91, v83, s37
	v_bfe_u32 v84, v93, 16, 1
	v_lshrrev_b32_e32 v83, 16, v83
	v_add3_u32 v84, v93, v84, s37
	v_and_or_b32 v83, v84, s38, v83
	v_bfe_u32 v84, v95, 16, 1
	v_add3_u32 v84, v95, v84, s37
	v_bfe_u32 v85, v97, 16, 1
	v_lshrrev_b32_e32 v84, 16, v84
	v_add3_u32 v85, v97, v85, s37
	v_and_or_b32 v84, v85, s38, v84
	v_bfe_u32 v85, v99, 16, 1
	v_add3_u32 v85, v99, v85, s37
	v_lshrrev_b32_e32 v85, 16, v85
	v_and_or_b32 v85, v86, s38, v85
	v_add_u32_e32 v86, s15, v76
	v_mad_i64_i32 v[86:87], s[28:29], v86, s41, 0
	v_lshl_add_u64 v[86:87], v[86:87], 1, s[18:19]
	v_lshl_add_u64 v[86:87], v[86:87], 0, s[12:13]
	ds_read2_b32 v[88:89], v75 offset0:16 offset1:24
	v_lshl_add_u64 v[86:87], v[86:87], 0, v[34:35]
	global_store_dwordx4 v[86:87], v[82:85], off nt
	ds_read2_b32 v[86:87], v75 offset0:49 offset1:57
	ds_read2_b32 v[90:91], v75 offset0:82 offset1:90
	ds_read2_b32 v[92:93], v75 offset0:115 offset1:123
	s_waitcnt lgkmcnt(3)
	v_bfe_u32 v82, v88, 16, 1
	v_add3_u32 v82, v88, v82, s37
	s_waitcnt lgkmcnt(2)
	v_bfe_u32 v83, v86, 16, 1
	ds_read2_b32 v[94:95], v75 offset0:148 offset1:156
	v_lshrrev_b32_e32 v82, 16, v82
	v_add3_u32 v83, v86, v83, s37
	ds_read2_b32 v[96:97], v75 offset0:181 offset1:189
	v_and_or_b32 v82, v83, s38, v82
	s_waitcnt lgkmcnt(3)
	v_bfe_u32 v83, v90, 16, 1
	v_add3_u32 v83, v90, v83, s37
	s_waitcnt lgkmcnt(2)
	v_bfe_u32 v84, v92, 16, 1
	ds_read2_b32 v[98:99], v75 offset0:214 offset1:222
	v_lshrrev_b32_e32 v83, 16, v83
	v_add3_u32 v84, v92, v84, s37
	ds_read2_b32 v[100:101], v75 offset0:247 offset1:255
	v_and_or_b32 v83, v84, s38, v83
	s_waitcnt lgkmcnt(3)
	v_bfe_u32 v84, v94, 16, 1
	v_add3_u32 v84, v94, v84, s37
	s_waitcnt lgkmcnt(2)
	v_bfe_u32 v85, v96, 16, 1
	v_lshrrev_b32_e32 v84, 16, v84
	v_add3_u32 v85, v96, v85, s37
	v_and_or_b32 v84, v85, s38, v84
	s_waitcnt lgkmcnt(1)
	v_bfe_u32 v85, v98, 16, 1
	v_add3_u32 v85, v98, v85, s37
	s_waitcnt lgkmcnt(0)
	v_bfe_u32 v86, v100, 16, 1
	v_lshrrev_b32_e32 v85, 16, v85
	v_add3_u32 v86, v100, v86, s37
	v_and_or_b32 v85, v86, s38, v85
	v_add_u32_e32 v86, s15, v77
	v_mad_i64_i32 v[102:103], s[28:29], v86, s41, 0
	v_lshl_add_u64 v[102:103], v[102:103], 1, s[18:19]
	v_lshl_add_u64 v[102:103], v[102:103], 0, s[12:13]
	v_lshl_add_u64 v[102:103], v[102:103], 0, v[34:35]
	global_store_dwordx4 v[102:103], v[82:85], off nt
	v_bfe_u32 v86, v101, 16, 1
	v_add3_u32 v86, v101, v86, s37
	v_bfe_u32 v82, v89, 16, 1
	v_add3_u32 v82, v89, v82, s37
	v_bfe_u32 v83, v87, 16, 1
	v_lshrrev_b32_e32 v82, 16, v82
	v_add3_u32 v83, v87, v83, s37
	v_and_or_b32 v82, v83, s38, v82
	v_bfe_u32 v83, v91, 16, 1
	v_add3_u32 v83, v91, v83, s37
	v_bfe_u32 v84, v93, 16, 1
	v_lshrrev_b32_e32 v83, 16, v83
	v_add3_u32 v84, v93, v84, s37
	v_and_or_b32 v83, v84, s38, v83
	v_bfe_u32 v84, v95, 16, 1
	v_add3_u32 v84, v95, v84, s37
	v_bfe_u32 v85, v97, 16, 1
	v_lshrrev_b32_e32 v84, 16, v84
	v_add3_u32 v85, v97, v85, s37
	v_and_or_b32 v84, v85, s38, v84
	v_bfe_u32 v85, v99, 16, 1
	v_add3_u32 v85, v99, v85, s37
	v_lshrrev_b32_e32 v85, 16, v85
	v_and_or_b32 v85, v86, s38, v85
	v_add_u32_e32 v86, s15, v78
	v_mad_i64_i32 v[86:87], s[28:29], v86, s41, 0
	v_lshl_add_u64 v[86:87], v[86:87], 1, s[18:19]
	v_lshl_add_u64 v[86:87], v[86:87], 0, s[12:13]
	v_lshl_add_u64 v[86:87], v[86:87], 0, v[34:35]
	global_store_dwordx4 v[86:87], v[82:85], off nt
	s_waitcnt lgkmcnt(0)
	s_and_b64 s[12:13], s[26:27], exec
	s_cselect_b32 s39, s5, s39
	s_branch .LBB0_28

.LBB0_81:
	s_mov_b64 s[4:5], s[98:99]
	s_add_i32 s16, s14, 0xffe00000
	s_mov_b64 s[6:7], s[98:99]
	s_lshl_b64 s[34:35], s[16:17], 2
	s_add_u32 s4, s4, s34
	s_mov_b32 s15, s17
	s_addc_u32 s5, s5, s35
	s_lshl_b64 s[34:35], s[14:15], 2
	v_lshl_add_u64 v[34:35], s[4:5], 0, v[66:67]
	s_add_u32 s4, s6, s34
	global_load_dwordx4 v[62:65], v[34:35], off nt
	global_load_dwordx4 v[58:61], v[34:35], off offset:1024 nt
	global_load_dwordx4 v[50:53], v[34:35], off offset:2048 nt
	global_load_dwordx4 v[54:57], v[34:35], off offset:3072 nt
	s_addc_u32 s5, s7, s35
	v_lshl_add_u64 v[70:71], s[4:5], 0, v[66:67]
	global_load_dwordx4 v[46:49], v[70:71], off nt
	global_load_dwordx4 v[42:45], v[70:71], off offset:1024 nt
	global_load_dwordx4 v[38:41], v[70:71], off offset:2048 nt
	global_load_dwordx4 v[34:37], v[70:71], off offset:3072 nt
	s_mov_b64 s[36:37], s[0:1]
	s_load_dwordx2 s[4:5], s[36:37], 0x80
	s_lshl_b64 s[34:35], s[16:17], 1
	s_mov_b64 s[18:19], s[0:1]
	s_mov_b64 s[20:21], s[0:1]
	s_mov_b64 s[22:23], s[0:1]
	s_waitcnt lgkmcnt(0)
	s_add_u32 s4, s4, s34
	s_addc_u32 s5, s5, s35
	v_lshl_add_u64 v[70:71], s[4:5], 0, v[68:69]
	v_add_co_u32_e32 v70, vcc, s39, v70
	s_lshl_b64 s[36:37], s[14:15], 1
	s_nop 0
	v_addc_co_u32_e32 v71, vcc, 0, v71, vcc
	s_mov_b64 s[24:25], s[0:1]
	s_mov_b64 s[26:27], s[0:1]
	s_mov_b64 s[28:29], s[0:1]
	s_mov_b64 s[30:31], s[0:1]
	s_waitcnt vmcnt(7)
	v_mov_b32_e32 v74, v63
	v_mov_b32_e32 v75, v64
	v_mov_b32_e32 v76, v62
	v_mov_b32_e32 v77, v65
	s_waitcnt vmcnt(6)
	v_mov_b32_e32 v78, v59
	v_mov_b32_e32 v79, v60
	v_mov_b32_e32 v80, v58
	v_mov_b32_e32 v81, v61
	s_waitcnt vmcnt(5)
	v_add_f32_e32 v82, v50, v51
	v_add_f32_e32 v84, v52, v53
	s_waitcnt vmcnt(4)
	v_mov_b32_e32 v83, v56
	v_mov_b32_e32 v85, v57
	v_pk_add_f32 v[74:75], v[74:75], v[76:77]
	v_pk_add_f32 v[76:77], v[78:79], v[80:81]
	v_pk_add_f32 v[78:79], v[82:83], v[84:85]
	v_add_f32_e32 v86, v74, v75
	s_waitcnt vmcnt(3)
	v_mov_b32_e32 v74, v47
	v_mov_b32_e32 v75, v48
	v_mov_b32_e32 v80, v46
	v_mov_b32_e32 v81, v49
	v_pk_add_f32 v[76:77], v[76:77], v[76:77] op_sel:[0,1] op_sel_hi:[1,0]
	s_waitcnt vmcnt(2)
	v_mov_b32_e32 v82, v43
	v_mov_b32_e32 v83, v44
	v_mov_b32_e32 v84, v42
	v_mov_b32_e32 v85, v45
	v_mov_b32_e32 v87, v54
	v_add_f32_e32 v86, 0, v86
	v_pk_add_f32 v[74:75], v[74:75], v[80:81]
	v_pk_add_f32 v[80:81], v[82:83], v[84:85]
	v_mov_b32_e32 v77, v55
	v_add_f32_e32 v84, v74, v75
	v_pk_add_f32 v[74:75], v[80:81], v[80:81] op_sel:[0,1] op_sel_hi:[1,0]
	v_pk_add_f32 v[76:77], v[86:87], v[76:77]
	s_waitcnt vmcnt(1)
	v_add_f32_e32 v88, v38, v39
	v_add_f32_e32 v90, v40, v41
	s_waitcnt vmcnt(0)
	v_mov_b32_e32 v93, v34
	v_mov_b32_e32 v89, v36
	v_mov_b32_e32 v91, v37
	v_add_f32_e32 v92, 0, v84
	v_pk_add_f32 v[76:77], v[76:77], v[78:79]
	v_mov_b32_e32 v75, v35
	v_pk_add_f32 v[82:83], v[88:89], v[90:91]
	v_add_f32_e32 v76, v76, v77
	v_pk_add_f32 v[74:75], v[92:93], v[74:75]
	v_pk_add_f32 v[74:75], v[74:75], v[82:83]
	s_nop 0
	v_add_f32_e32 v74, v74, v75
	s_nop 1
	v_add_f32_dpp v76, v76, v76 quad_perm:[1,0,3,2] row_mask:0xf bank_mask:0xf
	v_add_f32_dpp v74, v74, v74 quad_perm:[1,0,3,2] row_mask:0xf bank_mask:0xf
	s_nop 1
	v_add_f32_dpp v76, v76, v76 quad_perm:[2,3,0,1] row_mask:0xf bank_mask:0xf
	v_add_f32_dpp v74, v74, v74 quad_perm:[2,3,0,1] row_mask:0xf bank_mask:0xf
	s_nop 1
	v_add_f32_dpp v76, v76, v76 row_ror:4 row_mask:0xf bank_mask:0xf
	v_add_f32_dpp v74, v74, v74 row_ror:4 row_mask:0xf bank_mask:0xf
	s_nop 1
	v_add_f32_dpp v76, v76, v76 row_ror:8 row_mask:0xf bank_mask:0xf
	v_add_f32_dpp v74, v74, v74 row_ror:8 row_mask:0xf bank_mask:0xf
	s_nop 1
	v_mov_b32_e32 v77, v76
	v_mov_b32_e32 v75, v74
	s_nop 1
	v_permlane16_swap_b32_e32 v77, v76
	v_permlane16_swap_b32_e32 v75, v74
	s_nop 1
	v_add_f32_e32 v76, v77, v76
	v_add_f32_e32 v74, v75, v74
	v_mov_b32_e32 v77, v76
	v_mov_b32_e32 v75, v74
	s_nop 1
	v_permlane32_swap_b32_e32 v77, v76
	v_permlane32_swap_b32_e32 v75, v74
	s_nop 1
	v_add_f32_e32 v76, v77, v76
	v_add_f32_e32 v74, v75, v74
	v_fmamk_f32 v63, v76, 0xba800000, v63
	v_fmamk_f32 v62, v76, 0xba800000, v62
	v_fmamk_f32 v65, v76, 0xba800000, v65
	v_fmac_f32_e32 v64, 0xba800000, v76
	v_fmamk_f32 v59, v76, 0xba800000, v59
	v_fmamk_f32 v58, v76, 0xba800000, v58
	v_fmamk_f32 v61, v76, 0xba800000, v61
	v_fmac_f32_e32 v60, 0xba800000, v76
	v_fmamk_f32 v51, v76, 0xba800000, v51
	v_fmamk_f32 v50, v76, 0xba800000, v50
	v_fmamk_f32 v53, v76, 0xba800000, v53
	v_fmac_f32_e32 v52, 0xba800000, v76
	v_fmamk_f32 v57, v76, 0xba800000, v57
	v_fmamk_f32 v56, v76, 0xba800000, v56
	v_fmamk_f32 v55, v76, 0xba800000, v55
	v_fmac_f32_e32 v54, 0xba800000, v76
	v_mov_b32_e32 v83, v74
	v_pk_mul_f32 v[74:75], v[64:65], v[64:65]
	v_pk_mul_f32 v[76:77], v[62:63], v[62:63]
	v_pk_mul_f32 v[78:79], v[60:61], v[60:61]
	v_pk_mul_f32 v[80:81], v[58:59], v[58:59]
	v_pk_mov_b32 v[86:87], v[76:77], v[74:75] op_sel:[1,0]
	v_mov_b32_e32 v77, v75
	v_pk_mov_b32 v[74:75], v[80:81], v[78:79] op_sel:[1,0]
	v_mov_b32_e32 v81, v79
	v_mul_f32_e32 v82, v51, v51
	v_mul_f32_e32 v84, v53, v53
	v_fmamk_f32 v47, v83, 0xba800000, v47
	v_fmamk_f32 v46, v83, 0xba800000, v46
	v_fmamk_f32 v49, v83, 0xba800000, v49
	v_fmac_f32_e32 v48, 0xba800000, v83
	v_fmamk_f32 v43, v83, 0xba800000, v43
	v_fmamk_f32 v42, v83, 0xba800000, v42
	v_fmamk_f32 v45, v83, 0xba800000, v45
	v_fmac_f32_e32 v44, 0xba800000, v83
	v_pk_add_f32 v[76:77], v[86:87], v[76:77]
	v_pk_add_f32 v[74:75], v[74:75], v[80:81]
	v_mul_f32_e32 v91, v54, v54
	v_mul_f32_e32 v93, v55, v55
	v_mul_f32_e32 v90, v56, v56
	v_mul_f32_e32 v92, v57, v57
	v_fmamk_f32 v39, v83, 0xba800000, v39
	v_fmamk_f32 v38, v83, 0xba800000, v38
	v_fmamk_f32 v41, v83, 0xba800000, v41
	v_fmac_f32_e32 v40, 0xba800000, v83
	v_fmamk_f32 v37, v83, 0xba800000, v37
	v_fmamk_f32 v36, v83, 0xba800000, v36
	v_fmamk_f32 v35, v83, 0xba800000, v35
	v_fmac_f32_e32 v34, 0xba800000, v83
	v_pk_fma_f32 v[78:79], v[50:51], v[50:51], v[82:83] op_sel_hi:[1,1,0]
	v_pk_fma_f32 v[82:83], v[52:53], v[52:53], v[84:85] op_sel_hi:[1,1,0]
	v_pk_mul_f32 v[84:85], v[48:49], v[48:49]
	v_pk_mul_f32 v[86:87], v[46:47], v[46:47]
	v_pk_mul_f32 v[80:81], v[44:45], v[44:45]
	v_pk_mul_f32 v[88:89], v[42:43], v[42:43]
	v_pk_add_f32 v[76:77], v[76:77], v[76:77] op_sel:[0,1] op_sel_hi:[1,0]
	v_pk_add_f32 v[74:75], v[74:75], v[74:75] op_sel:[0,1] op_sel_hi:[1,0]
	v_mov_b32_e32 v79, v90
	v_mov_b32_e32 v83, v92
	v_pk_mov_b32 v[94:95], v[86:87], v[84:85] op_sel:[1,0]
	v_mov_b32_e32 v87, v85
	v_pk_mov_b32 v[84:85], v[88:89], v[80:81] op_sel:[1,0]
	v_mov_b32_e32 v89, v81
	v_mov_b32_e32 v77, v91
	v_mov_b32_e32 v75, v93
	v_mul_f32_e32 v90, v39, v39
	v_mul_f32_e32 v92, v41, v41
	v_pk_add_f32 v[78:79], v[78:79], v[82:83]
	v_pk_add_f32 v[86:87], v[94:95], v[86:87]
	v_pk_add_f32 v[84:85], v[84:85], v[88:89]
	v_pk_add_f32 v[74:75], v[76:77], v[74:75]
	v_mul_f32_e32 v96, v34, v34
	v_mul_f32_e32 v97, v35, v35
	v_mul_f32_e32 v98, v36, v36
	v_mul_f32_e32 v99, v37, v37
	v_pk_fma_f32 v[80:81], v[38:39], v[38:39], v[90:91] op_sel_hi:[1,1,0]
	v_pk_fma_f32 v[82:83], v[40:41], v[40:41], v[92:93] op_sel_hi:[1,1,0]
	v_pk_add_f32 v[76:77], v[86:87], v[86:87] op_sel:[0,1] op_sel_hi:[1,0]
	v_pk_add_f32 v[84:85], v[84:85], v[84:85] op_sel:[0,1] op_sel_hi:[1,0]
	v_pk_add_f32 v[74:75], v[74:75], v[78:79]
	v_mov_b32_e32 v81, v98
	v_mov_b32_e32 v83, v99
	v_mov_b32_e32 v77, v96
	v_mov_b32_e32 v85, v97
	v_add_f32_e32 v78, v74, v75
	v_pk_add_f32 v[80:81], v[80:81], v[82:83]
	v_pk_add_f32 v[74:75], v[76:77], v[84:85]
	v_pk_add_f32 v[74:75], v[74:75], v[80:81]
	v_mov_b32_e32 v76, v78
	s_nop 0
	v_add_f32_e32 v74, v74, v75
	s_nop 1
	v_add_f32_dpp v76, v76, v76 quad_perm:[1,0,3,2] row_mask:0xf bank_mask:0xf
	v_add_f32_dpp v74, v74, v74 quad_perm:[1,0,3,2] row_mask:0xf bank_mask:0xf
	s_nop 1
	v_add_f32_dpp v76, v76, v76 quad_perm:[2,3,0,1] row_mask:0xf bank_mask:0xf
	v_add_f32_dpp v74, v74, v74 quad_perm:[2,3,0,1] row_mask:0xf bank_mask:0xf
	s_nop 1
	v_add_f32_dpp v76, v76, v76 row_ror:4 row_mask:0xf bank_mask:0xf
	v_add_f32_dpp v74, v74, v74 row_ror:4 row_mask:0xf bank_mask:0xf
	s_nop 1
	v_add_f32_dpp v76, v76, v76 row_ror:8 row_mask:0xf bank_mask:0xf
	v_add_f32_dpp v74, v74, v74 row_ror:8 row_mask:0xf bank_mask:0xf
	s_nop 1
	v_mov_b32_e32 v77, v76
	v_mov_b32_e32 v75, v74
	s_nop 1
	v_permlane16_swap_b32_e32 v77, v76
	v_permlane16_swap_b32_e32 v75, v74
	s_nop 1
	v_add_f32_e32 v76, v77, v76
	v_add_f32_e32 v74, v75, v74
	v_mov_b32_e32 v77, v76
	v_mov_b32_e32 v75, v74
	s_nop 1
	v_permlane32_swap_b32_e32 v77, v76
	v_permlane32_swap_b32_e32 v75, v74
	s_nop 1
	v_add_f32_e32 v76, v77, v76
	v_add_f32_e32 v74, v75, v74
	v_fmamk_f32 v76, v76, 0x3a800000, v72
	v_mul_f32_e32 v77, 0x4f800000, v76
	v_cmp_gt_f32_e32 vcc, s33, v76
	v_fmamk_f32 v74, v74, 0x3a800000, v72
	v_cndmask_b32_e32 v75, v76, v77, vcc
	v_sqrt_f32_e32 v76, v75
	v_mul_f32_e32 v77, 0x4f800000, v74
	v_cmp_gt_f32_e64 s[4:5], s33, v74
	v_add_u32_e32 v78, -1, v76
	s_nop 0
	v_cndmask_b32_e64 v74, v74, v77, s[4:5]
	v_sqrt_f32_e32 v77, v74
	v_add_u32_e32 v79, 1, v76
	v_fma_f32 v80, -v78, v76, v75
	v_fma_f32 v81, -v79, v76, v75
	v_cmp_ge_f32_e64 s[6:7], 0, v80
	v_add_u32_e32 v80, 1, v77
	s_nop 0
	v_cndmask_b32_e64 v76, v76, v78, s[6:7]
	v_add_u32_e32 v78, -1, v77
	v_cmp_lt_f32_e64 s[6:7], 0, v81
	v_fma_f32 v81, -v80, v77, v74
	s_nop 0
	v_cndmask_b32_e64 v76, v76, v79, s[6:7]
	v_fma_f32 v79, -v78, v77, v74
	v_cmp_ge_f32_e64 s[6:7], 0, v79
	v_mul_f32_e32 v82, 0x37800000, v76
	v_cndmask_b32_e32 v76, v76, v82, vcc
	v_cndmask_b32_e64 v77, v77, v78, s[6:7]
	v_cmp_lt_f32_e64 s[6:7], 0, v81
	v_cmp_class_f32_e32 vcc, v75, v73
	s_nop 0
	v_cndmask_b32_e64 v77, v77, v80, s[6:7]
	v_cndmask_b32_e32 v75, v76, v75, vcc
	v_mul_f32_e32 v76, 0x37800000, v77
	v_div_scale_f32 v78, s[6:7], v75, v75, 1.0
	v_cndmask_b32_e64 v76, v77, v76, s[4:5]
	v_cmp_class_f32_e64 s[4:5], v74, v73
	v_rcp_f32_e32 v77, v78
	v_div_scale_f32 v79, vcc, 1.0, v75, 1.0
	v_cndmask_b32_e64 v76, v76, v74, s[4:5]
	v_div_scale_f32 v80, s[4:5], v76, v76, 1.0
	v_rcp_f32_e32 v82, v80
	v_fma_f32 v74, -v78, v77, 1.0
	v_fmac_f32_e32 v77, v74, v77
	v_mul_f32_e32 v74, v79, v77
	v_fma_f32 v83, -v80, v82, 1.0
	v_div_scale_f32 v81, s[4:5], 1.0, v76, 1.0
	v_fma_f32 v84, -v78, v74, v79
	v_fmac_f32_e32 v82, v83, v82
	v_fmac_f32_e32 v74, v84, v77
	v_mul_f32_e32 v83, v81, v82
	v_fma_f32 v78, -v78, v74, v79
	v_fma_f32 v79, -v80, v83, v81
	v_div_fmas_f32 v74, v78, v77, v74
	v_fmac_f32_e32 v83, v79, v82
	v_div_fixup_f32 v74, v74, v75, 1.0
	v_fma_f32 v75, -v80, v83, v81
	s_mov_b64 vcc, s[4:5]
	v_div_fmas_f32 v75, v75, v82, v83
	v_pk_mul_f32 v[62:63], v[74:75], v[62:63] op_sel_hi:[0,1]
	v_pk_mul_f32 v[64:65], v[74:75], v[64:65] op_sel_hi:[0,1]
	v_pk_mul_f32 v[58:59], v[74:75], v[58:59] op_sel_hi:[0,1]
	v_pk_mul_f32 v[60:61], v[74:75], v[60:61] op_sel_hi:[0,1]
	v_pk_mul_f32 v[50:51], v[74:75], v[50:51] op_sel_hi:[0,1]
	v_pk_mul_f32 v[52:53], v[74:75], v[52:53] op_sel_hi:[0,1]
	v_pk_mul_f32 v[54:55], v[74:75], v[54:55] op_sel_hi:[0,1]
	v_pk_mul_f32 v[56:57], v[74:75], v[56:57] op_sel_hi:[0,1]
	v_div_fixup_f32 v74, v75, v76, 1.0
	v_pk_fma_f32 v[64:65], v[4:5], v[64:65], v[8:9]
	v_pk_fma_f32 v[62:63], v[2:3], v[62:63], v[6:7]
	v_pk_fma_f32 v[52:53], v[20:21], v[52:53], v[24:25]
	v_pk_fma_f32 v[50:51], v[18:19], v[50:51], v[22:23]
	v_pk_fma_f32 v[56:57], v[28:29], v[56:57], v[32:33]
	v_pk_fma_f32 v[54:55], v[26:27], v[54:55], v[30:31]
	v_pk_mul_f32 v[46:47], v[74:75], v[46:47] op_sel_hi:[0,1]
	v_pk_mul_f32 v[48:49], v[74:75], v[48:49] op_sel_hi:[0,1]
	v_bfe_u32 v75, v62, 16, 1
	v_bfe_u32 v77, v64, 16, 1
	v_pk_fma_f32 v[60:61], v[12:13], v[60:61], v[16:17]
	v_bfe_u32 v76, v63, 16, 1
	v_bfe_u32 v78, v65, 16, 1
	v_pk_mul_f32 v[42:43], v[74:75], v[42:43] op_sel_hi:[0,1]
	v_pk_mul_f32 v[44:45], v[74:75], v[44:45] op_sel_hi:[0,1]
	v_pk_mul_f32 v[38:39], v[74:75], v[38:39] op_sel_hi:[0,1]
	v_pk_mul_f32 v[40:41], v[74:75], v[40:41] op_sel_hi:[0,1]
	v_bfe_u32 v83, v50, 16, 1
	v_bfe_u32 v84, v51, 16, 1
	v_bfe_u32 v85, v52, 16, 1
	v_bfe_u32 v86, v53, 16, 1
	v_pk_mul_f32 v[34:35], v[74:75], v[34:35] op_sel_hi:[0,1]
	v_pk_mul_f32 v[36:37], v[74:75], v[36:37] op_sel_hi:[0,1]
	v_bfe_u32 v74, v54, 16, 1
	v_bfe_u32 v87, v55, 16, 1
	v_bfe_u32 v88, v56, 16, 1
	v_bfe_u32 v89, v57, 16, 1
	v_add3_u32 v62, v62, v75, s12
	v_add3_u32 v64, v64, v77, s12
	v_bfe_u32 v82, v61, 16, 1
	v_add3_u32 v63, v63, v76, s12
	v_add3_u32 v65, v65, v78, s12
	v_add3_u32 v50, v50, v83, s12
	v_add3_u32 v75, v51, v84, s12
	v_add3_u32 v51, v52, v85, s12
	v_add3_u32 v52, v53, v86, s12
	v_add3_u32 v53, v54, v74, s12
	v_add3_u32 v54, v55, v87, s12
	v_add3_u32 v55, v56, v88, s12
	v_add3_u32 v56, v57, v89, s12
	v_lshrrev_b32_e32 v57, 16, v62
	v_lshrrev_b32_e32 v62, 16, v64
	v_add3_u32 v61, v61, v82, s12
	v_lshrrev_b32_e32 v82, 16, v50
	v_lshrrev_b32_e32 v83, 16, v51
	v_and_or_b32 v50, v63, s38, v57
	v_and_or_b32 v51, v65, s38, v62
	global_store_dwordx2 v[70:71], v[50:51], off nt
	s_load_dwordx2 s[4:5], s[18:19], 0x80
	v_pk_fma_f32 v[58:59], v[10:11], v[58:59], v[14:15]
	v_pk_fma_f32 v[48:49], v[4:5], v[48:49], v[8:9]
	v_bfe_u32 v79, v58, 16, 1
	v_bfe_u32 v80, v59, 16, 1
	v_pk_fma_f32 v[46:47], v[2:3], v[46:47], v[6:7]
	v_pk_fma_f32 v[42:43], v[10:11], v[42:43], v[14:15]
	v_add3_u32 v58, v58, v79, s12
	v_bfe_u32 v81, v60, 16, 1
	v_add3_u32 v59, v59, v80, s12
	v_pk_fma_f32 v[38:39], v[18:19], v[38:39], v[22:23]
	v_pk_fma_f32 v[36:37], v[28:29], v[36:37], v[32:33]
	v_pk_fma_f32 v[34:35], v[26:27], v[34:35], v[30:31]
	v_bfe_u32 v64, v46, 16, 1
	v_bfe_u32 v76, v48, 16, 1
	v_lshrrev_b32_e32 v58, 16, v58
	v_bfe_u32 v78, v42, 16, 1
	v_add3_u32 v60, v60, v81, s12
	v_bfe_u32 v74, v47, 16, 1
	v_bfe_u32 v77, v49, 16, 1
	v_bfe_u32 v79, v43, 16, 1
	v_bfe_u32 v84, v38, 16, 1
	v_lshrrev_b32_e32 v53, 16, v53
	v_bfe_u32 v88, v34, 16, 1
	v_bfe_u32 v89, v35, 16, 1
	v_bfe_u32 v90, v36, 16, 1
	v_bfe_u32 v91, v37, 16, 1
	v_add3_u32 v57, v46, v64, s12
	v_add3_u32 v48, v48, v76, s12
	v_and_or_b32 v46, v59, s38, v58
	v_add3_u32 v58, v42, v78, s12
	s_waitcnt lgkmcnt(0)
	s_add_u32 s4, s4, s36
	v_lshrrev_b32_e32 v60, 16, v60
	v_bfe_u32 v85, v39, 16, 1
	v_lshrrev_b32_e32 v55, 16, v55
	v_add3_u32 v62, v47, v74, s12
	v_add3_u32 v49, v49, v77, s12
	v_add3_u32 v59, v43, v79, s12
	v_and_or_b32 v43, v52, s38, v83
	v_add3_u32 v52, v38, v84, s12
	v_and_or_b32 v38, v54, s38, v53
	v_add3_u32 v34, v34, v88, s12
	v_add3_u32 v53, v35, v89, s12
	v_add3_u32 v35, v36, v90, s12
	v_add3_u32 v54, v37, v91, s12
	v_lshrrev_b32_e32 v36, 16, v57
	v_lshrrev_b32_e32 v37, 16, v48
	v_lshrrev_b32_e32 v48, 16, v58
	s_addc_u32 s5, s5, s37
	v_and_or_b32 v47, v61, s38, v60
	v_add3_u32 v60, v39, v85, s12
	v_and_or_b32 v39, v56, s38, v55
	v_lshrrev_b32_e32 v50, 16, v52
	v_lshrrev_b32_e32 v52, 16, v34
	v_lshrrev_b32_e32 v55, 16, v35
	v_and_or_b32 v34, v62, s38, v36
	v_and_or_b32 v35, v49, s38, v37
	v_and_or_b32 v36, v59, s38, v48
	v_lshl_add_u64 v[48:49], s[4:5], 0, v[68:69]
	v_add_co_u32_e32 v48, vcc, s39, v48
	v_pk_fma_f32 v[44:45], v[12:13], v[44:45], v[16:17]
	s_nop 0
	v_addc_co_u32_e32 v49, vcc, 0, v49, vcc
	global_store_dwordx2 v[48:49], v[34:35], off nt
	s_load_dwordx2 s[4:5], s[20:21], 0x80
	v_bfe_u32 v80, v44, 16, 1
	v_bfe_u32 v81, v45, 16, 1
	v_add3_u32 v44, v44, v80, s12
	v_add3_u32 v45, v45, v81, s12
	s_waitcnt lgkmcnt(0)
	s_add_u32 s4, s4, s34
	s_addc_u32 s5, s5, s35
	v_lshl_add_u64 v[34:35], s[4:5], 0, v[68:69]
	v_add_co_u32_e32 v34, vcc, s39, v34
	v_lshrrev_b32_e32 v44, 16, v44
	s_nop 0
	v_addc_co_u32_e32 v35, vcc, 0, v35, vcc
	global_store_dwordx2 v[34:35], v[46:47], off offset:512 nt
	s_load_dwordx2 s[4:5], s[22:23], 0x80
	v_and_or_b32 v37, v45, s38, v44
	v_and_or_b32 v42, v75, s38, v82
	v_pk_fma_f32 v[40:41], v[20:21], v[40:41], v[24:25]
	v_and_or_b32 v44, v53, s38, v52
	s_waitcnt lgkmcnt(0)
	s_add_u32 s4, s4, s36
	s_addc_u32 s5, s5, s37
	v_lshl_add_u64 v[34:35], s[4:5], 0, v[68:69]
	v_add_co_u32_e32 v34, vcc, s39, v34
	v_bfe_u32 v86, v40, 16, 1
	s_nop 0
	v_addc_co_u32_e32 v35, vcc, 0, v35, vcc
	global_store_dwordx2 v[34:35], v[36:37], off offset:512 nt
	s_load_dwordx2 s[4:5], s[24:25], 0x80
	v_bfe_u32 v87, v41, 16, 1
	v_add3_u32 v40, v40, v86, s12
	v_add3_u32 v41, v41, v87, s12
	v_lshrrev_b32_e32 v51, 16, v40
	s_waitcnt lgkmcnt(0)
	s_add_u32 s4, s4, s34
	s_addc_u32 s5, s5, s35
	v_lshl_add_u64 v[34:35], s[4:5], 0, v[68:69]
	v_add_co_u32_e32 v34, vcc, s39, v34
	v_and_or_b32 v40, v60, s38, v50
	s_nop 0
	v_addc_co_u32_e32 v35, vcc, 0, v35, vcc
	global_store_dwordx2 v[34:35], v[42:43], off offset:1024 nt
	s_load_dwordx2 s[4:5], s[26:27], 0x80
	v_and_or_b32 v41, v41, s38, v51
	v_and_or_b32 v45, v54, s38, v55
	s_waitcnt lgkmcnt(0)
	s_add_u32 s4, s4, s36
	s_addc_u32 s5, s5, s37
	v_lshl_add_u64 v[34:35], s[4:5], 0, v[68:69]
	v_add_co_u32_e32 v34, vcc, s39, v34
	s_nop 1
	v_addc_co_u32_e32 v35, vcc, 0, v35, vcc
	global_store_dwordx2 v[34:35], v[40:41], off offset:1024 nt
	s_load_dwordx2 s[4:5], s[28:29], 0x80
	s_waitcnt lgkmcnt(0)
	s_add_u32 s4, s4, s34
	s_addc_u32 s5, s5, s35
	v_lshl_add_u64 v[34:35], s[4:5], 0, v[68:69]
	v_add_co_u32_e32 v34, vcc, s39, v34
	s_nop 1
	v_addc_co_u32_e32 v35, vcc, 0, v35, vcc
	global_store_dwordx2 v[34:35], v[38:39], off offset:1536 nt
	s_load_dwordx2 s[4:5], s[30:31], 0x80
	s_waitcnt lgkmcnt(0)
	s_add_u32 s4, s4, s36
	s_addc_u32 s5, s5, s37
	v_lshl_add_u64 v[34:35], s[4:5], 0, v[68:69]
	s_addk_i32 s13, 0x1000
	s_add_i32 s14, s14, 0x400000
	v_add_co_u32_e32 v34, vcc, 0x7200000, v34
	s_cmpk_gt_u32 s13, 0x6fff
	s_nop 0
	v_addc_co_u32_e32 v35, vcc, 0, v35, vcc
	global_store_dwordx2 v[34:35], v[44:45], off offset:1536 nt
	s_cbranch_scc0 .LBB0_81
